# v16 + hand-written SwiGLU epilogue (packed f32 math, saddr stores, all row scales read up front)
# speedup vs baseline: 1.0090x; 1.0021x over previous
; __device__ __forceinline__ unsigned cvt_pk_bf16(float lo, float hi) { unsigned r; asm volatile("v_cvt_pk_bf16_f32 %0, %1, %2" : "=v"(r) : "v"(lo), "v"(hi)); return r; }
;     __device__ __forceinline__ void operator()(const f32x4 (&acc)[2][2][4][2], const pg8::Unit& u, int wr, int wc, int fr, int fq) const {
;         const int row0 = u.pm * 256 + wr * 64 + fr, col0 = u.pn * 128 + wc * 32 + 8 * fq;
; #pragma unroll
;         for (int ai = 0; ai < 2; ++ai)
; #pragma unroll
;             for (int m = 0; m < 4; ++m) {
;                 bf16_t* p = Hd + (size_t)(row0 + ai * 128 + m * 16) * FF + col0;
;                 const float rsc = scr[u.idx * 256 + wr * 64 + fr + ai * 128 + m * 16];
;                 const float nrl = -rsc * LOG2E, ir2 = __builtin_amdgcn_rcpf(rsc * rsc);
;                 float h[8];
; #pragma unroll
;                 for (int n = 0; n < 2; ++n)
; #pragma unroll
;                     for (int j = 0; j < 4; ++j) { const float ag = acc[ai][0][m][n][j], au = acc[ai][1][m][n][j];
;                         const float e = __builtin_amdgcn_exp2f(ag * nrl);
;                         h[n * 4 + j] = (ag * au) * __builtin_amdgcn_rcpf(__builtin_fmaf(e, ir2, ir2)); }
;                 u32x4 w; w.x = pg8::cvt_pk_bf16(h[0], h[1]); w.y = pg8::cvt_pk_bf16(h[2], h[3]); w.z = pg8::cvt_pk_bf16(h[4], h[5]); w.w = pg8::cvt_pk_bf16(h[6], h[7]);
;                 *(u32x4*)p = w;
.LBB0_783:
	v_readlane_b32 s68, v254, 15
	v_readlane_b32 s69, v254, 16
	v_lshl_add_u32 v174, s77, 10, v146
	v_lshl_add_u32 v172, s66, 8, v81
	v_lshl_or_b32 v168, s76, 7, v147
	ds_read_b32 v160, v174
	ds_read_b32 v161, v174 offset:64
	ds_read_b32 v162, v174 offset:128
	ds_read_b32 v163, v174 offset:192
	ds_read_b32 v164, v174 offset:512
	ds_read_b32 v165, v174 offset:576
	ds_read_b32 v166, v174 offset:640
	ds_read_b32 v167, v174 offset:704
	v_mul_u32_u24_e32 v173, s97, v172
	v_lshl_add_u32 v173, v168, 1, v173
	s_waitcnt lgkmcnt(0)
	v_mul_f32_e32 v156, 0xbfb8aa3b, v160
	v_mul_f32_e32 v158, v160, v160
	v_add_u32_e32 v172, 0x0, v173
	v_rcp_f32_e32 v158, v158
	v_pk_mul_f32 v[148:149], v[126:127], v[156:157] op_sel_hi:[1,0]
	v_pk_mul_f32 v[150:151], v[128:129], v[156:157] op_sel_hi:[1,0]
	v_pk_mul_f32 v[152:153], v[118:119], v[156:157] op_sel_hi:[1,0]
	v_pk_mul_f32 v[154:155], v[120:121], v[156:157] op_sel_hi:[1,0]
	v_exp_f32_e32 v148, v148
	v_exp_f32_e32 v149, v149
	v_exp_f32_e32 v150, v150
	v_exp_f32_e32 v151, v151
	v_exp_f32_e32 v152, v152
	v_exp_f32_e32 v153, v153
	v_exp_f32_e32 v154, v154
	v_exp_f32_e32 v155, v155
	v_pk_mul_f32 v[122:123], v[126:127], v[122:123]
	v_pk_mul_f32 v[124:125], v[128:129], v[124:125]
	v_pk_mul_f32 v[114:115], v[118:119], v[114:115]
	v_pk_mul_f32 v[116:117], v[120:121], v[116:117]
	v_pk_fma_f32 v[148:149], v[148:149], v[158:159], v[158:159] op_sel_hi:[1,0,0]
	v_pk_fma_f32 v[150:151], v[150:151], v[158:159], v[158:159] op_sel_hi:[1,0,0]
	v_pk_fma_f32 v[152:153], v[152:153], v[158:159], v[158:159] op_sel_hi:[1,0,0]
	v_pk_fma_f32 v[154:155], v[154:155], v[158:159], v[158:159] op_sel_hi:[1,0,0]
	v_rcp_f32_e32 v148, v148
	v_rcp_f32_e32 v149, v149
	v_rcp_f32_e32 v150, v150
	v_rcp_f32_e32 v151, v151
	v_rcp_f32_e32 v152, v152
	v_rcp_f32_e32 v153, v153
	v_rcp_f32_e32 v154, v154
	v_rcp_f32_e32 v155, v155
	s_nop 0
	v_pk_mul_f32 v[122:123], v[122:123], v[148:149]
	v_pk_mul_f32 v[124:125], v[124:125], v[150:151]
	v_pk_mul_f32 v[114:115], v[114:115], v[152:153]
	v_pk_mul_f32 v[116:117], v[116:117], v[154:155]
	v_cvt_pk_bf16_f32 v168, v122, v123
	v_cvt_pk_bf16_f32 v169, v124, v125
	v_cvt_pk_bf16_f32 v170, v114, v115
	v_cvt_pk_bf16_f32 v171, v116, v117
	global_store_dwordx4 v172, v[168:171], s[68:69]
	v_mul_f32_e32 v156, 0xbfb8aa3b, v161
	v_mul_f32_e32 v158, v161, v161
	v_add_u32_e32 v172, 0x16000, v173
	v_rcp_f32_e32 v158, v158
	v_pk_mul_f32 v[148:149], v[110:111], v[156:157] op_sel_hi:[1,0]
	v_pk_mul_f32 v[150:151], v[112:113], v[156:157] op_sel_hi:[1,0]
	v_pk_mul_f32 v[152:153], v[102:103], v[156:157] op_sel_hi:[1,0]
	v_pk_mul_f32 v[154:155], v[104:105], v[156:157] op_sel_hi:[1,0]
	v_exp_f32_e32 v148, v148
	v_exp_f32_e32 v149, v149
	v_exp_f32_e32 v150, v150
	v_exp_f32_e32 v151, v151
	v_exp_f32_e32 v152, v152
	v_exp_f32_e32 v153, v153
	v_exp_f32_e32 v154, v154
	v_exp_f32_e32 v155, v155
	v_pk_mul_f32 v[106:107], v[110:111], v[106:107]
	v_pk_mul_f32 v[108:109], v[112:113], v[108:109]
	v_pk_mul_f32 v[98:99], v[102:103], v[98:99]
	v_pk_mul_f32 v[100:101], v[104:105], v[100:101]
	v_pk_fma_f32 v[148:149], v[148:149], v[158:159], v[158:159] op_sel_hi:[1,0,0]
	v_pk_fma_f32 v[150:151], v[150:151], v[158:159], v[158:159] op_sel_hi:[1,0,0]
	v_pk_fma_f32 v[152:153], v[152:153], v[158:159], v[158:159] op_sel_hi:[1,0,0]
	v_pk_fma_f32 v[154:155], v[154:155], v[158:159], v[158:159] op_sel_hi:[1,0,0]
	v_rcp_f32_e32 v148, v148
	v_rcp_f32_e32 v149, v149
	v_rcp_f32_e32 v150, v150
	v_rcp_f32_e32 v151, v151
	v_rcp_f32_e32 v152, v152
	v_rcp_f32_e32 v153, v153
	v_rcp_f32_e32 v154, v154
	v_rcp_f32_e32 v155, v155
	s_nop 0
	v_pk_mul_f32 v[106:107], v[106:107], v[148:149]
	v_pk_mul_f32 v[108:109], v[108:109], v[150:151]
	v_pk_mul_f32 v[98:99], v[98:99], v[152:153]
	v_pk_mul_f32 v[100:101], v[100:101], v[154:155]
	v_cvt_pk_bf16_f32 v168, v106, v107
	v_cvt_pk_bf16_f32 v169, v108, v109
	v_cvt_pk_bf16_f32 v170, v98, v99
	v_cvt_pk_bf16_f32 v171, v100, v101
	global_store_dwordx4 v172, v[168:171], s[68:69]
	v_mul_f32_e32 v156, 0xbfb8aa3b, v162
	v_mul_f32_e32 v158, v162, v162
	v_add_u32_e32 v172, 0x2c000, v173
	v_rcp_f32_e32 v158, v158
	v_pk_mul_f32 v[148:149], v[94:95], v[156:157] op_sel_hi:[1,0]
	v_pk_mul_f32 v[150:151], v[96:97], v[156:157] op_sel_hi:[1,0]
	v_pk_mul_f32 v[152:153], v[86:87], v[156:157] op_sel_hi:[1,0]
	v_pk_mul_f32 v[154:155], v[88:89], v[156:157] op_sel_hi:[1,0]
	v_exp_f32_e32 v148, v148
	v_exp_f32_e32 v149, v149
	v_exp_f32_e32 v150, v150
	v_exp_f32_e32 v151, v151
	v_exp_f32_e32 v152, v152
	v_exp_f32_e32 v153, v153
	v_exp_f32_e32 v154, v154
	v_exp_f32_e32 v155, v155
	v_pk_mul_f32 v[90:91], v[94:95], v[90:91]
	v_pk_mul_f32 v[92:93], v[96:97], v[92:93]
	v_pk_mul_f32 v[82:83], v[86:87], v[82:83]
	v_pk_mul_f32 v[84:85], v[88:89], v[84:85]
	v_pk_fma_f32 v[148:149], v[148:149], v[158:159], v[158:159] op_sel_hi:[1,0,0]
	v_pk_fma_f32 v[150:151], v[150:151], v[158:159], v[158:159] op_sel_hi:[1,0,0]
	v_pk_fma_f32 v[152:153], v[152:153], v[158:159], v[158:159] op_sel_hi:[1,0,0]
	v_pk_fma_f32 v[154:155], v[154:155], v[158:159], v[158:159] op_sel_hi:[1,0,0]
	v_rcp_f32_e32 v148, v148
	v_rcp_f32_e32 v149, v149
	v_rcp_f32_e32 v150, v150
	v_rcp_f32_e32 v151, v151
	v_rcp_f32_e32 v152, v152
	v_rcp_f32_e32 v153, v153
	v_rcp_f32_e32 v154, v154
	v_rcp_f32_e32 v155, v155
	s_nop 0
	v_pk_mul_f32 v[90:91], v[90:91], v[148:149]
	v_pk_mul_f32 v[92:93], v[92:93], v[150:151]
	v_pk_mul_f32 v[82:83], v[82:83], v[152:153]
	v_pk_mul_f32 v[84:85], v[84:85], v[154:155]
	v_cvt_pk_bf16_f32 v168, v90, v91
	v_cvt_pk_bf16_f32 v169, v92, v93
	v_cvt_pk_bf16_f32 v170, v82, v83
	v_cvt_pk_bf16_f32 v171, v84, v85
	global_store_dwordx4 v172, v[168:171], s[68:69]
	v_mul_f32_e32 v156, 0xbfb8aa3b, v163
; __device__ __forceinline__ unsigned cvt_pk_bf16(float lo, float hi) { unsigned r; asm volatile("v_cvt_pk_bf16_f32 %0, %1, %2" : "=v"(r) : "v"(lo), "v"(hi)); return r; }
;     __device__ __forceinline__ void operator()(const f32x4 (&acc)[2][2][4][2], const pg8::Unit& u, int wr, int wc, int fr, int fq) const {
;     ...
;             for (int m = 0; m < 4; ++m) {
;                 bf16_t* p = Hd + (size_t)(row0 + ai * 128 + m * 16) * FF + col0;
;                 const float rsc = scr[u.idx * 256 + wr * 64 + fr + ai * 128 + m * 16];
;                 const float nrl = -rsc * LOG2E, ir2 = __builtin_amdgcn_rcpf(rsc * rsc);
;                 float h[8];
; #pragma unroll
;                 for (int n = 0; n < 2; ++n)
; #pragma unroll
;                     for (int j = 0; j < 4; ++j) { const float ag = acc[ai][0][m][n][j], au = acc[ai][1][m][n][j];
;                         const float e = __builtin_amdgcn_exp2f(ag * nrl);
;                         h[n * 4 + j] = (ag * au) * __builtin_amdgcn_rcpf(__builtin_fmaf(e, ir2, ir2)); }
;                 u32x4 w; w.x = pg8::cvt_pk_bf16(h[0], h[1]); w.y = pg8::cvt_pk_bf16(h[2], h[3]); w.z = pg8::cvt_pk_bf16(h[4], h[5]); w.w = pg8::cvt_pk_bf16(h[6], h[7]);
;                 *(u32x4*)p = w;
	v_mul_f32_e32 v158, v163, v163
	v_add_u32_e32 v172, 0x42000, v173
	v_rcp_f32_e32 v158, v158
	v_pk_mul_f32 v[148:149], v[76:77], v[156:157] op_sel_hi:[1,0]
	v_pk_mul_f32 v[150:151], v[78:79], v[156:157] op_sel_hi:[1,0]
	v_pk_mul_f32 v[152:153], v[68:69], v[156:157] op_sel_hi:[1,0]
	v_pk_mul_f32 v[154:155], v[70:71], v[156:157] op_sel_hi:[1,0]
	v_exp_f32_e32 v148, v148
	v_exp_f32_e32 v149, v149
	v_exp_f32_e32 v150, v150
	v_exp_f32_e32 v151, v151
	v_exp_f32_e32 v152, v152
	v_exp_f32_e32 v153, v153
	v_exp_f32_e32 v154, v154
	v_exp_f32_e32 v155, v155
	v_pk_mul_f32 v[72:73], v[76:77], v[72:73]
	v_pk_mul_f32 v[74:75], v[78:79], v[74:75]
	v_pk_mul_f32 v[64:65], v[68:69], v[64:65]
	v_pk_mul_f32 v[66:67], v[70:71], v[66:67]
	v_pk_fma_f32 v[148:149], v[148:149], v[158:159], v[158:159] op_sel_hi:[1,0,0]
	v_pk_fma_f32 v[150:151], v[150:151], v[158:159], v[158:159] op_sel_hi:[1,0,0]
	v_pk_fma_f32 v[152:153], v[152:153], v[158:159], v[158:159] op_sel_hi:[1,0,0]
	v_pk_fma_f32 v[154:155], v[154:155], v[158:159], v[158:159] op_sel_hi:[1,0,0]
	v_rcp_f32_e32 v148, v148
	v_rcp_f32_e32 v149, v149
	v_rcp_f32_e32 v150, v150
	v_rcp_f32_e32 v151, v151
	v_rcp_f32_e32 v152, v152
	v_rcp_f32_e32 v153, v153
	v_rcp_f32_e32 v154, v154
	v_rcp_f32_e32 v155, v155
	s_nop 0
	v_pk_mul_f32 v[72:73], v[72:73], v[148:149]
	v_pk_mul_f32 v[74:75], v[74:75], v[150:151]
	v_pk_mul_f32 v[64:65], v[64:65], v[152:153]
	v_pk_mul_f32 v[66:67], v[66:67], v[154:155]
	v_cvt_pk_bf16_f32 v168, v72, v73
	v_cvt_pk_bf16_f32 v169, v74, v75
	v_cvt_pk_bf16_f32 v170, v64, v65
	v_cvt_pk_bf16_f32 v171, v66, v67
	global_store_dwordx4 v172, v[168:171], s[68:69]
	v_mul_f32_e32 v156, 0xbfb8aa3b, v164
	v_mul_f32_e32 v158, v164, v164
	v_add_u32_e32 v172, 0xb0000, v173
	v_rcp_f32_e32 v158, v158
	v_pk_mul_f32 v[148:149], v[60:61], v[156:157] op_sel_hi:[1,0]
	v_pk_mul_f32 v[150:151], v[62:63], v[156:157] op_sel_hi:[1,0]
	v_pk_mul_f32 v[152:153], v[52:53], v[156:157] op_sel_hi:[1,0]
	v_pk_mul_f32 v[154:155], v[54:55], v[156:157] op_sel_hi:[1,0]
	v_exp_f32_e32 v148, v148
	v_exp_f32_e32 v149, v149
	v_exp_f32_e32 v150, v150
	v_exp_f32_e32 v151, v151
	v_exp_f32_e32 v152, v152
	v_exp_f32_e32 v153, v153
	v_exp_f32_e32 v154, v154
	v_exp_f32_e32 v155, v155
	v_pk_mul_f32 v[56:57], v[60:61], v[56:57]
	v_pk_mul_f32 v[58:59], v[62:63], v[58:59]
	v_pk_mul_f32 v[48:49], v[52:53], v[48:49]
	v_pk_mul_f32 v[50:51], v[54:55], v[50:51]
	v_pk_fma_f32 v[148:149], v[148:149], v[158:159], v[158:159] op_sel_hi:[1,0,0]
	v_pk_fma_f32 v[150:151], v[150:151], v[158:159], v[158:159] op_sel_hi:[1,0,0]
	v_pk_fma_f32 v[152:153], v[152:153], v[158:159], v[158:159] op_sel_hi:[1,0,0]
	v_pk_fma_f32 v[154:155], v[154:155], v[158:159], v[158:159] op_sel_hi:[1,0,0]
	v_rcp_f32_e32 v148, v148
	v_rcp_f32_e32 v149, v149
	v_rcp_f32_e32 v150, v150
	v_rcp_f32_e32 v151, v151
	v_rcp_f32_e32 v152, v152
	v_rcp_f32_e32 v153, v153
	v_rcp_f32_e32 v154, v154
	v_rcp_f32_e32 v155, v155
	s_nop 0
	v_pk_mul_f32 v[56:57], v[56:57], v[148:149]
	v_pk_mul_f32 v[58:59], v[58:59], v[150:151]
	v_pk_mul_f32 v[48:49], v[48:49], v[152:153]
	v_pk_mul_f32 v[50:51], v[50:51], v[154:155]
	v_cvt_pk_bf16_f32 v168, v56, v57
	v_cvt_pk_bf16_f32 v169, v58, v59
	v_cvt_pk_bf16_f32 v170, v48, v49
	v_cvt_pk_bf16_f32 v171, v50, v51
	global_store_dwordx4 v172, v[168:171], s[68:69]
	v_mul_f32_e32 v156, 0xbfb8aa3b, v165
	v_mul_f32_e32 v158, v165, v165
	v_add_u32_e32 v172, 0xc6000, v173
	v_rcp_f32_e32 v158, v158
	v_pk_mul_f32 v[148:149], v[44:45], v[156:157] op_sel_hi:[1,0]
	v_pk_mul_f32 v[150:151], v[46:47], v[156:157] op_sel_hi:[1,0]
	v_pk_mul_f32 v[152:153], v[36:37], v[156:157] op_sel_hi:[1,0]
	v_pk_mul_f32 v[154:155], v[38:39], v[156:157] op_sel_hi:[1,0]
	v_exp_f32_e32 v148, v148
	v_exp_f32_e32 v149, v149
	v_exp_f32_e32 v150, v150
	v_exp_f32_e32 v151, v151
	v_exp_f32_e32 v152, v152
	v_exp_f32_e32 v153, v153
	v_exp_f32_e32 v154, v154
	v_exp_f32_e32 v155, v155
	v_pk_mul_f32 v[40:41], v[44:45], v[40:41]
	v_pk_mul_f32 v[42:43], v[46:47], v[42:43]
	v_pk_mul_f32 v[32:33], v[36:37], v[32:33]
	v_pk_mul_f32 v[34:35], v[38:39], v[34:35]
	v_pk_fma_f32 v[148:149], v[148:149], v[158:159], v[158:159] op_sel_hi:[1,0,0]
	v_pk_fma_f32 v[150:151], v[150:151], v[158:159], v[158:159] op_sel_hi:[1,0,0]
; __device__ __forceinline__ unsigned cvt_pk_bf16(float lo, float hi) { unsigned r; asm volatile("v_cvt_pk_bf16_f32 %0, %1, %2" : "=v"(r) : "v"(lo), "v"(hi)); return r; }
; template <class Epi, class Sched, bool ALIGN_EPI = false, bool SP2 = false>
; __device__ __forceinline__ void gemm_phase(PG8_LAS unsigned char* lds, const Gemm g, const Sched& S, const Epi& E, int tid_in) {
;     ...
;         if constexpr (!Epi::AFTER_DRAIN) { E(acc, cur, wr, wc, fr, fq); S.done(cur); }
;         if (!has_next) break;
;     __device__ __forceinline__ void operator()(const f32x4 (&acc)[2][2][4][2], const pg8::Unit& u, int wr, int wc, int fr, int fq) const {
;     ...
;             for (int m = 0; m < 4; ++m) {
;                 bf16_t* p = Hd + (size_t)(row0 + ai * 128 + m * 16) * FF + col0;
;                 const float rsc = scr[u.idx * 256 + wr * 64 + fr + ai * 128 + m * 16];
;                 const float nrl = -rsc * LOG2E, ir2 = __builtin_amdgcn_rcpf(rsc * rsc);
;                 float h[8];
; #pragma unroll
;                 for (int n = 0; n < 2; ++n)
; #pragma unroll
;                     for (int j = 0; j < 4; ++j) { const float ag = acc[ai][0][m][n][j], au = acc[ai][1][m][n][j];
;                         const float e = __builtin_amdgcn_exp2f(ag * nrl);
;                         h[n * 4 + j] = (ag * au) * __builtin_amdgcn_rcpf(__builtin_fmaf(e, ir2, ir2)); }
;                 u32x4 w; w.x = pg8::cvt_pk_bf16(h[0], h[1]); w.y = pg8::cvt_pk_bf16(h[2], h[3]); w.z = pg8::cvt_pk_bf16(h[4], h[5]); w.w = pg8::cvt_pk_bf16(h[6], h[7]);
;                 *(u32x4*)p = w;
;             }
;     }
	v_pk_fma_f32 v[152:153], v[152:153], v[158:159], v[158:159] op_sel_hi:[1,0,0]
	v_pk_fma_f32 v[154:155], v[154:155], v[158:159], v[158:159] op_sel_hi:[1,0,0]
	v_rcp_f32_e32 v148, v148
	v_rcp_f32_e32 v149, v149
	v_rcp_f32_e32 v150, v150
	v_rcp_f32_e32 v151, v151
	v_rcp_f32_e32 v152, v152
	v_rcp_f32_e32 v153, v153
	v_rcp_f32_e32 v154, v154
	v_rcp_f32_e32 v155, v155
	s_nop 0
	v_pk_mul_f32 v[40:41], v[40:41], v[148:149]
	v_pk_mul_f32 v[42:43], v[42:43], v[150:151]
	v_pk_mul_f32 v[32:33], v[32:33], v[152:153]
	v_pk_mul_f32 v[34:35], v[34:35], v[154:155]
	v_cvt_pk_bf16_f32 v168, v40, v41
	v_cvt_pk_bf16_f32 v169, v42, v43
	v_cvt_pk_bf16_f32 v170, v32, v33
	v_cvt_pk_bf16_f32 v171, v34, v35
	global_store_dwordx4 v172, v[168:171], s[68:69]
	v_mul_f32_e32 v156, 0xbfb8aa3b, v166
	v_mul_f32_e32 v158, v166, v166
	v_add_u32_e32 v172, 0xdc000, v173
	v_rcp_f32_e32 v158, v158
	v_pk_mul_f32 v[148:149], v[28:29], v[156:157] op_sel_hi:[1,0]
	v_pk_mul_f32 v[150:151], v[30:31], v[156:157] op_sel_hi:[1,0]
	v_pk_mul_f32 v[152:153], v[20:21], v[156:157] op_sel_hi:[1,0]
	v_pk_mul_f32 v[154:155], v[22:23], v[156:157] op_sel_hi:[1,0]
	v_exp_f32_e32 v148, v148
	v_exp_f32_e32 v149, v149
	v_exp_f32_e32 v150, v150
	v_exp_f32_e32 v151, v151
	v_exp_f32_e32 v152, v152
	v_exp_f32_e32 v153, v153
	v_exp_f32_e32 v154, v154
	v_exp_f32_e32 v155, v155
	v_pk_mul_f32 v[24:25], v[28:29], v[24:25]
	v_pk_mul_f32 v[26:27], v[30:31], v[26:27]
	v_pk_mul_f32 v[16:17], v[20:21], v[16:17]
	v_pk_mul_f32 v[18:19], v[22:23], v[18:19]
	v_pk_fma_f32 v[148:149], v[148:149], v[158:159], v[158:159] op_sel_hi:[1,0,0]
	v_pk_fma_f32 v[150:151], v[150:151], v[158:159], v[158:159] op_sel_hi:[1,0,0]
	v_pk_fma_f32 v[152:153], v[152:153], v[158:159], v[158:159] op_sel_hi:[1,0,0]
	v_pk_fma_f32 v[154:155], v[154:155], v[158:159], v[158:159] op_sel_hi:[1,0,0]
	v_rcp_f32_e32 v148, v148
	v_rcp_f32_e32 v149, v149
	v_rcp_f32_e32 v150, v150
	v_rcp_f32_e32 v151, v151
	v_rcp_f32_e32 v152, v152
	v_rcp_f32_e32 v153, v153
	v_rcp_f32_e32 v154, v154
	v_rcp_f32_e32 v155, v155
	s_nop 0
	v_pk_mul_f32 v[24:25], v[24:25], v[148:149]
	v_pk_mul_f32 v[26:27], v[26:27], v[150:151]
	v_pk_mul_f32 v[16:17], v[16:17], v[152:153]
	v_pk_mul_f32 v[18:19], v[18:19], v[154:155]
	v_cvt_pk_bf16_f32 v168, v24, v25
	v_cvt_pk_bf16_f32 v169, v26, v27
	v_cvt_pk_bf16_f32 v170, v16, v17
	v_cvt_pk_bf16_f32 v171, v18, v19
	global_store_dwordx4 v172, v[168:171], s[68:69]
	v_mul_f32_e32 v156, 0xbfb8aa3b, v167
	v_mul_f32_e32 v158, v167, v167
	v_add_u32_e32 v172, 0xf2000, v173
	v_rcp_f32_e32 v158, v158
	v_pk_mul_f32 v[148:149], v[12:13], v[156:157] op_sel_hi:[1,0]
	v_pk_mul_f32 v[150:151], v[14:15], v[156:157] op_sel_hi:[1,0]
	v_pk_mul_f32 v[152:153], v[4:5], v[156:157] op_sel_hi:[1,0]
	v_pk_mul_f32 v[154:155], v[6:7], v[156:157] op_sel_hi:[1,0]
	v_exp_f32_e32 v148, v148
	v_exp_f32_e32 v149, v149
	v_exp_f32_e32 v150, v150
	v_exp_f32_e32 v151, v151
	v_exp_f32_e32 v152, v152
	v_exp_f32_e32 v153, v153
	v_exp_f32_e32 v154, v154
	v_exp_f32_e32 v155, v155
	v_pk_mul_f32 v[8:9], v[12:13], v[8:9]
	v_pk_mul_f32 v[10:11], v[14:15], v[10:11]
	v_pk_mul_f32 v[0:1], v[4:5], v[0:1]
	v_pk_mul_f32 v[2:3], v[6:7], v[2:3]
	v_pk_fma_f32 v[148:149], v[148:149], v[158:159], v[158:159] op_sel_hi:[1,0,0]
	v_pk_fma_f32 v[150:151], v[150:151], v[158:159], v[158:159] op_sel_hi:[1,0,0]
	v_pk_fma_f32 v[152:153], v[152:153], v[158:159], v[158:159] op_sel_hi:[1,0,0]
	v_pk_fma_f32 v[154:155], v[154:155], v[158:159], v[158:159] op_sel_hi:[1,0,0]
	v_rcp_f32_e32 v148, v148
	v_rcp_f32_e32 v149, v149
	v_rcp_f32_e32 v150, v150
	v_rcp_f32_e32 v151, v151
	v_rcp_f32_e32 v152, v152
	v_rcp_f32_e32 v153, v153
	v_rcp_f32_e32 v154, v154
	v_rcp_f32_e32 v155, v155
	s_nop 0
	v_pk_mul_f32 v[8:9], v[8:9], v[148:149]
	v_pk_mul_f32 v[10:11], v[10:11], v[150:151]
	v_pk_mul_f32 v[0:1], v[0:1], v[152:153]
	v_pk_mul_f32 v[2:3], v[2:3], v[154:155]
	v_cvt_pk_bf16_f32 v168, v8, v9
	v_cvt_pk_bf16_f32 v169, v10, v11
	v_cvt_pk_bf16_f32 v170, v0, v1
	v_cvt_pk_bf16_f32 v171, v2, v3
	global_store_dwordx4 v172, v[168:171], s[68:69]
	s_andn2_b64 vcc, exec, s[36:37]
	s_mov_b64 s[36:37], -1
	s_cbranch_vccnz .LBB0_776
	s_andn2_b64 vcc, exec, s[38:39]
	s_cbranch_vccnz .LBB0_775
	s_barrier
	s_branch .LBB0_775
